# v080 + all UP epilogue ACT stores write-through (sc1)
# speedup vs baseline: 1.0033x; 1.0017x over previous
.LBB0_1348:
	s_waitcnt lgkmcnt(0)
	v_cndmask_b32_e64 v18, v140, v18, s[42:43]
	v_cndmask_b32_e64 v19, v141, v19, s[42:43]
	v_cndmask_b32_e64 v136, v140, v124, s[40:41]
	v_mov_b32_dpp v18, v18 row_ror:1 row_mask:0xf bank_mask:0xf
	v_cndmask_b32_e64 v137, v141, v125, s[40:41]
	v_mov_b32_dpp v19, v19 row_ror:1 row_mask:0xf bank_mask:0xf
	v_mov_b32_dpp v136, v136 row_ror:15 row_mask:0xf bank_mask:0xf
	v_mov_b32_dpp v137, v137 row_ror:15 row_mask:0xf bank_mask:0xf
	v_cndmask_b32_e64 v14, v130, v14, s[40:41]
	s_nop 1
	v_mov_b32_dpp v166, v14 row_ror:15 row_mask:0xf bank_mask:0xf
	v_cndmask_b32_e64 v14, v131, v109, s[42:43]
	v_cndmask_b32_e64 v15, v131, v15, s[40:41]
	v_cndmask_b32_e64 v139, v124, v140, s[42:43]
	v_cndmask_b32_e64 v145, v125, v141, s[42:43]
	v_mov_b32_dpp v167, v14 row_ror:1 row_mask:0xf bank_mask:0xf
	v_mov_b32_dpp v168, v15 row_ror:15 row_mask:0xf bank_mask:0xf
	s_waitcnt lgkmcnt(0)
	v_cndmask_b32_e64 v15, v19, 0, s[58:59]
	v_cndmask_b32_e64 v14, v18, 0, s[58:59]
	v_pk_mul_f32 v[140:141], v[140:141], v[22:23]
	v_cndmask_b32_e64 v19, v137, 0, s[44:45]
	v_cndmask_b32_e64 v18, v136, 0, s[44:45]
	v_pk_fma_f32 v[14:15], v[2:3], v[14:15], v[140:141]
	v_cndmask_b32_e64 v144, v124, v108, s[40:41]
	v_pk_fma_f32 v[14:15], v[6:7], v[18:19], v[14:15]
	v_mov_b32_dpp v139, v139 row_ror:1 row_mask:0xf bank_mask:0xf
	v_pk_add_f32 v[14:15], v[10:11], v[14:15]
	v_cndmask_b32_e64 v146, v125, v109, s[40:41]
	v_mul_f32_e32 v18, 0xbfb8aa3b, v14
	v_mul_f32_e32 v19, 0xbfb8aa3b, v15
	v_exp_f32_e32 v18, v18
	v_exp_f32_e32 v19, v19
	v_mov_b32_dpp v145, v145 row_ror:1 row_mask:0xf bank_mask:0xf
	v_mov_b32_dpp v144, v144 row_ror:15 row_mask:0xf bank_mask:0xf
	v_mov_b32_dpp v146, v146 row_ror:15 row_mask:0xf bank_mask:0xf
	v_pk_add_f32 v[18:19], v[18:19], 1.0 op_sel_hi:[1,0]
	v_cndmask_b32_e64 v147, v108, v124, s[42:43]
	v_rcp_f32_e32 v18, v18
	v_rcp_f32_e32 v19, v19
	v_cndmask_b32_e64 v163, v109, v125, s[42:43]
	v_pk_mul_f32 v[124:125], v[124:125], v[22:23]
	s_waitcnt lgkmcnt(0)
	v_cndmask_b32_e64 v141, v146, 0, s[46:47]
	v_pk_mul_f32 v[14:15], v[14:15], v[18:19]
	v_cndmask_b32_e64 v19, v145, 0, s[48:49]
	v_cndmask_b32_e64 v18, v139, 0, s[48:49]
	v_cndmask_b32_e64 v140, v144, 0, s[46:47]
	v_pk_fma_f32 v[18:19], v[2:3], v[18:19], v[124:125]
	v_cndmask_b32_e64 v162, v108, v130, s[40:41]
	v_pk_fma_f32 v[18:19], v[6:7], v[140:141], v[18:19]
	v_mov_b32_dpp v147, v147 row_ror:1 row_mask:0xf bank_mask:0xf
	v_pk_add_f32 v[18:19], v[10:11], v[18:19]
	v_cndmask_b32_e64 v164, v109, v131, s[40:41]
	v_mul_f32_e32 v124, 0xbfb8aa3b, v18
	v_mul_f32_e32 v125, 0xbfb8aa3b, v19
	v_exp_f32_e32 v124, v124
	v_exp_f32_e32 v125, v125
	v_mov_b32_dpp v163, v163 row_ror:1 row_mask:0xf bank_mask:0xf
	v_mov_b32_dpp v162, v162 row_ror:15 row_mask:0xf bank_mask:0xf
	v_mov_b32_dpp v164, v164 row_ror:15 row_mask:0xf bank_mask:0xf
	v_pk_add_f32 v[124:125], v[124:125], 1.0 op_sel_hi:[1,0]
	v_cndmask_b32_e64 v165, v130, v108, s[42:43]
	v_rcp_f32_e32 v124, v124
	v_rcp_f32_e32 v125, v125
	v_pk_mul_f32 v[108:109], v[108:109], v[22:23]
	v_mov_b32_dpp v165, v165 row_ror:1 row_mask:0xf bank_mask:0xf
	v_pk_mul_f32 v[22:23], v[130:131], v[22:23]
	v_pk_mul_f32 v[18:19], v[18:19], v[124:125]
	s_waitcnt lgkmcnt(0)
	v_cndmask_b32_e64 v125, v164, 0, s[50:51]
	v_pk_mul_f32 v[18:19], v[116:117], v[18:19]
	v_cndmask_b32_e64 v117, v163, 0, s[52:53]
	v_cndmask_b32_e64 v116, v147, 0, s[52:53]
	v_cndmask_b32_e64 v124, v162, 0, s[50:51]
	v_pk_fma_f32 v[108:109], v[2:3], v[116:117], v[108:109]
	v_pk_mul_f32 v[136:137], v[142:143], v[24:25]
	v_pk_fma_f32 v[108:109], v[6:7], v[124:125], v[108:109]
	v_cndmask_b32_e64 v16, v122, v16, s[40:41]
	v_pk_add_f32 v[108:109], v[10:11], v[108:109]
	v_pk_mul_f32 v[14:15], v[132:133], v[14:15]
	v_mul_f32_e32 v116, 0xbfb8aa3b, v108
	v_mul_f32_e32 v117, 0xbfb8aa3b, v109
	v_exp_f32_e32 v116, v116
	v_exp_f32_e32 v117, v117
	v_pk_mul_f32 v[132:133], v[126:127], v[24:25]
	v_pk_mul_f32 v[140:141], v[110:111], v[24:25]
	v_pk_mul_f32 v[24:25], v[122:123], v[24:25]
	v_pk_add_f32 v[116:117], v[116:117], 1.0 op_sel_hi:[1,0]
	v_cndmask_b32_e64 v17, v123, v17, s[40:41]
	v_rcp_f32_e32 v116, v116
	v_rcp_f32_e32 v117, v117
	v_lshl_or_b32 v138, s0, 7, v197
	s_movk_i32 s0, 0xfe
	v_pk_mul_f32 v[108:109], v[108:109], v[116:117]
	s_nop 0
	v_pk_mul_f32 v[106:107], v[106:107], v[108:109]
	v_cndmask_b32_e64 v109, v167, 0, s[54:55]
	v_cndmask_b32_e64 v108, v165, 0, s[54:55]
	v_cndmask_b32_e64 v117, v168, 0, s[56:57]
	v_cndmask_b32_e64 v116, v166, 0, s[56:57]
	v_pk_fma_f32 v[2:3], v[2:3], v[108:109], v[22:23]
	v_cndmask_b32_e64 v22, v127, v143, s[42:43]
	v_pk_fma_f32 v[2:3], v[6:7], v[116:117], v[2:3]
	v_cndmask_b32_e64 v23, v127, v111, s[40:41]
	v_pk_add_f32 v[2:3], v[10:11], v[2:3]
	v_cndmask_b32_e64 v11, v143, v127, s[40:41]
	v_mul_f32_e32 v6, 0xbfb8aa3b, v2
	v_mul_f32_e32 v7, 0xbfb8aa3b, v3
	v_exp_f32_e32 v6, v6
	v_exp_f32_e32 v7, v7
	v_mov_b32_dpp v11, v11 row_ror:15 row_mask:0xf bank_mask:0xf
	v_mov_b32_dpp v22, v22 row_ror:1 row_mask:0xf bank_mask:0xf
	v_mov_b32_dpp v23, v23 row_ror:15 row_mask:0xf bank_mask:0xf
	v_pk_add_f32 v[6:7], v[6:7], 1.0 op_sel_hi:[1,0]
	v_cndmask_b32_e64 v108, v110, v126, s[42:43]
	v_rcp_f32_e32 v6, v6
	v_rcp_f32_e32 v7, v7
	s_waitcnt lgkmcnt(0)
	v_cndmask_b32_e64 v11, v11, 0, s[44:45]
	v_cndmask_b32_e64 v109, v110, v122, s[40:41]
	v_cndmask_b32_e64 v116, v111, v127, s[42:43]
	v_pk_mul_f32 v[2:3], v[2:3], v[6:7]
	v_cndmask_b32_e64 v7, v142, v126, s[40:41]
	v_cndmask_b32_e64 v6, v142, v20, s[42:43]
	s_nop 0
	v_mov_b32_dpp v10, v7 row_ror:15 row_mask:0xf bank_mask:0xf
	v_cndmask_b32_e64 v7, v143, v21, s[42:43]
	v_mov_b32_dpp v6, v6 row_ror:1 row_mask:0xf bank_mask:0xf
	s_nop 0
	v_mov_b32_dpp v7, v7 row_ror:1 row_mask:0xf bank_mask:0xf
	v_cndmask_b32_e64 v20, v126, v142, s[42:43]
	s_waitcnt lgkmcnt(0)
	v_cndmask_b32_e64 v10, v10, 0, s[44:45]
	v_cndmask_b32_e64 v21, v126, v110, s[40:41]
	v_cndmask_b32_e64 v6, v6, 0, s[58:59]
	v_cndmask_b32_e64 v7, v7, 0, s[58:59]
	v_pk_fma_f32 v[6:7], v[4:5], v[6:7], v[136:137]
	v_mov_b32_dpp v20, v20 row_ror:1 row_mask:0xf bank_mask:0xf
	v_pk_fma_f32 v[6:7], v[8:9], v[10:11], v[6:7]
	v_mov_b32_dpp v21, v21 row_ror:15 row_mask:0xf bank_mask:0xf
	v_pk_add_f32 v[6:7], v[12:13], v[6:7]
	v_cndmask_b32_e64 v110, v122, v110, s[42:43]
	v_mul_f32_e32 v10, 0xbfb8aa3b, v6
	v_mul_f32_e32 v11, 0xbfb8aa3b, v7
	v_exp_f32_e32 v10, v10
	v_exp_f32_e32 v11, v11
	v_mov_b32_dpp v122, v16 row_ror:15 row_mask:0xf bank_mask:0xf
	v_cndmask_b32_e64 v16, v123, v111, s[42:43]
	v_cndmask_b32_e64 v117, v111, v123, s[40:41]
	v_pk_add_f32 v[10:11], v[10:11], 1.0 op_sel_hi:[1,0]
	v_mov_b32_dpp v111, v16 row_ror:1 row_mask:0xf bank_mask:0xf
	v_rcp_f32_e32 v10, v10
	v_rcp_f32_e32 v11, v11
	v_mov_b32_dpp v123, v17 row_ror:15 row_mask:0xf bank_mask:0xf
	v_cndmask_b32_e64 v17, v23, 0, s[46:47]
	s_waitcnt lgkmcnt(0)
	v_cndmask_b32_e64 v16, v21, 0, s[46:47]
	v_pk_mul_f32 v[6:7], v[6:7], v[10:11]
	v_cndmask_b32_e64 v11, v22, 0, s[48:49]
	v_cndmask_b32_e64 v10, v20, 0, s[48:49]
	v_pk_fma_f32 v[10:11], v[4:5], v[10:11], v[132:133]
	v_mov_b32_dpp v108, v108 row_ror:1 row_mask:0xf bank_mask:0xf
	v_pk_fma_f32 v[10:11], v[8:9], v[16:17], v[10:11]
	v_mov_b32_dpp v116, v116 row_ror:1 row_mask:0xf bank_mask:0xf
	v_pk_add_f32 v[10:11], v[12:13], v[10:11]
	v_mov_b32_dpp v109, v109 row_ror:15 row_mask:0xf bank_mask:0xf
	v_mul_f32_e32 v16, 0xbfb8aa3b, v10
	v_mul_f32_e32 v17, 0xbfb8aa3b, v11
	v_exp_f32_e32 v16, v16
	v_exp_f32_e32 v17, v17
	v_mov_b32_dpp v117, v117 row_ror:15 row_mask:0xf bank_mask:0xf
	s_waitcnt lgkmcnt(0)
	v_cndmask_b32_e64 v20, v109, 0, s[50:51]
	v_mov_b32_dpp v110, v110 row_ror:1 row_mask:0xf bank_mask:0xf
	v_pk_add_f32 v[16:17], v[16:17], 1.0 op_sel_hi:[1,0]
	v_cndmask_b32_e64 v23, v123, 0, s[56:57]
	v_rcp_f32_e32 v16, v16
	v_rcp_f32_e32 v17, v17
	v_cndmask_b32_e64 v21, v117, 0, s[50:51]
	v_cndmask_b32_e64 v22, v122, 0, s[56:57]
	v_pk_mul_f32 v[2:3], v[128:129], v[2:3]
	v_pk_mul_f32 v[10:11], v[10:11], v[16:17]
	v_cndmask_b32_e64 v17, v116, 0, s[52:53]
	v_cndmask_b32_e64 v16, v108, 0, s[52:53]
	v_pk_fma_f32 v[16:17], v[4:5], v[16:17], v[140:141]
	v_pk_mul_f32 v[6:7], v[134:135], v[6:7]
	v_pk_fma_f32 v[16:17], v[8:9], v[20:21], v[16:17]
	v_pk_mul_f32 v[10:11], v[118:119], v[10:11]
	v_pk_add_f32 v[16:17], v[12:13], v[16:17]
	s_nop 0
	v_mul_f32_e32 v20, 0xbfb8aa3b, v16
	v_mul_f32_e32 v21, 0xbfb8aa3b, v17
	v_exp_f32_e32 v20, v20
	v_exp_f32_e32 v21, v21
	s_nop 0
	v_pk_add_f32 v[20:21], v[20:21], 1.0 op_sel_hi:[1,0]
	s_nop 0
	v_rcp_f32_e32 v20, v20
	v_rcp_f32_e32 v21, v21
	s_nop 0
	v_pk_mul_f32 v[16:17], v[16:17], v[20:21]
	v_cndmask_b32_e64 v21, v111, 0, s[54:55]
	s_waitcnt lgkmcnt(0)
	v_cndmask_b32_e64 v20, v110, 0, s[54:55]
	v_pk_fma_f32 v[4:5], v[4:5], v[20:21], v[24:25]
	v_pk_mul_f32 v[16:17], v[102:103], v[16:17]
	v_pk_fma_f32 v[4:5], v[8:9], v[22:23], v[4:5]
	s_nop 0
	v_pk_add_f32 v[4:5], v[12:13], v[4:5]
	s_nop 0
	v_mul_f32_e32 v8, 0xbfb8aa3b, v4
	v_mul_f32_e32 v9, 0xbfb8aa3b, v5
	v_exp_f32_e32 v8, v8
	v_exp_f32_e32 v9, v9
	s_nop 0
	v_pk_add_f32 v[8:9], v[8:9], 1.0 op_sel_hi:[1,0]
	s_nop 0
	v_rcp_f32_e32 v8, v8
	v_rcp_f32_e32 v9, v9
	s_nop 0
	v_pk_mul_f32 v[4:5], v[4:5], v[8:9]
	v_add_u32_e32 v8, -1, v189
	v_cmp_gt_u32_e32 vcc, s0, v8
	v_cmp_gt_i32_e64 s[0:1], s10, v198
	v_pk_mul_f32 v[4:5], v[80:81], v[4:5]
	s_and_b64 s[58:59], vcc, s[0:1]
	s_and_saveexec_b64 s[0:1], s[58:59]
	s_cbranch_execz .LBB0_1350
	s_movk_i32 s58, 0xb00
	v_cvt_pk_bf16_f32 v14, v14, v15
	v_cvt_pk_bf16_f32 v15, v6, v7
	v_mul_lo_u32 v6, v198, s58
	v_cvt_pk_bf16_f32 v12, v82, v83
	v_cvt_pk_bf16_f32 v13, v90, v91
	v_add_lshl_u32 v6, v138, v6, 1
	global_store_dwordx4 v6, v[12:15], s[92:93] sc1
.LBB0_1350:
	s_or_b64 exec, exec, s[0:1]
	s_movk_i32 s0, 0xef
	v_cmp_gt_u32_e32 vcc, s0, v189
	v_cmp_gt_i32_e64 s[0:1], s10, v199
	s_and_b64 s[58:59], vcc, s[0:1]
	s_and_saveexec_b64 s[0:1], s[58:59]
	s_cbranch_execz .LBB0_1352
	s_movk_i32 s58, 0xb00
	v_cvt_pk_bf16_f32 v9, v10, v11
	v_mul_lo_u32 v10, v199, s58
	v_cvt_pk_bf16_f32 v6, v84, v85
	v_cvt_pk_bf16_f32 v7, v92, v93
	v_cvt_pk_bf16_f32 v8, v18, v19
	v_add_lshl_u32 v10, v138, v10, 1
	global_store_dwordx4 v10, v[6:9], s[92:93] sc1
.LBB0_1352:
	s_or_b64 exec, exec, s[0:1]
	s_movk_i32 s0, 0xdf
	v_cmp_gt_u32_e32 vcc, s0, v189
	v_cmp_gt_i32_e64 s[0:1], s10, v213
	s_and_b64 s[58:59], vcc, s[0:1]
	s_and_saveexec_b64 s[0:1], s[58:59]
	s_cbranch_execz .LBB0_1354
	s_movk_i32 s58, 0xb00
	v_mul_lo_u32 v10, v213, s58
	v_cvt_pk_bf16_f32 v6, v86, v87
	v_cvt_pk_bf16_f32 v7, v94, v95
	v_cvt_pk_bf16_f32 v8, v106, v107
	v_cvt_pk_bf16_f32 v9, v16, v17
	v_add_lshl_u32 v10, v138, v10, 1
	global_store_dwordx4 v10, v[6:9], s[92:93] sc1
.LBB0_1354:
	s_or_b64 exec, exec, s[0:1]
	s_movk_i32 s0, 0xcf
	v_cmp_gt_u32_e32 vcc, s0, v189
	v_cmp_gt_i32_e64 s[0:1], s10, v214
	s_and_b64 s[58:59], vcc, s[0:1]
	s_and_saveexec_b64 s[0:1], s[58:59]
	s_cbranch_execz .LBB0_1356
	s_movk_i32 s58, 0xb00
	v_cvt_pk_bf16_f32 v8, v2, v3
	v_mul_lo_u32 v2, v214, s58
	v_cvt_pk_bf16_f32 v6, v88, v89
	v_cvt_pk_bf16_f32 v7, v96, v97
	v_cvt_pk_bf16_f32 v9, v4, v5
	v_add_lshl_u32 v2, v138, v2, 1
	global_store_dwordx4 v2, v[6:9], s[92:93] sc1

.LBB0_1364:
	s_waitcnt lgkmcnt(0)
	v_cndmask_b32_e64 v18, v58, v18, s[42:43]
	v_cndmask_b32_e64 v19, v59, v19, s[42:43]
	v_cndmask_b32_e64 v68, v58, v42, s[40:41]
	v_mov_b32_dpp v18, v18 row_ror:1 row_mask:0xf bank_mask:0xf
	v_cndmask_b32_e64 v69, v59, v43, s[40:41]
	v_mov_b32_dpp v19, v19 row_ror:1 row_mask:0xf bank_mask:0xf
	v_mov_b32_dpp v68, v68 row_ror:15 row_mask:0xf bank_mask:0xf
	v_mov_b32_dpp v69, v69 row_ror:15 row_mask:0xf bank_mask:0xf
	v_cndmask_b32_e64 v14, v48, v14, s[40:41]
	s_nop 1
	v_mov_b32_dpp v85, v14 row_ror:15 row_mask:0xf bank_mask:0xf
	v_cndmask_b32_e64 v14, v49, v39, s[42:43]
	v_cndmask_b32_e64 v15, v49, v15, s[40:41]
	v_cndmask_b32_e64 v72, v42, v58, s[42:43]
	v_cndmask_b32_e64 v74, v43, v59, s[42:43]
	v_mov_b32_dpp v86, v14 row_ror:1 row_mask:0xf bank_mask:0xf
	v_mov_b32_dpp v87, v15 row_ror:15 row_mask:0xf bank_mask:0xf
	s_waitcnt lgkmcnt(0)
	v_cndmask_b32_e64 v15, 0, v19, s[46:47]
	v_cndmask_b32_e64 v14, 0, v18, s[46:47]
	v_pk_mul_f32 v[58:59], v[58:59], v[22:23]
	v_cndmask_b32_e64 v19, v69, 0, s[44:45]
	v_cndmask_b32_e64 v18, v68, 0, s[44:45]
	v_pk_fma_f32 v[14:15], v[2:3], v[14:15], v[58:59]
	v_cndmask_b32_e64 v73, v42, v38, s[40:41]
	v_pk_fma_f32 v[14:15], v[6:7], v[18:19], v[14:15]
	v_mov_b32_dpp v72, v72 row_ror:1 row_mask:0xf bank_mask:0xf
	v_pk_add_f32 v[14:15], v[10:11], v[14:15]
	v_cndmask_b32_e64 v75, v43, v39, s[40:41]
	v_mul_f32_e32 v18, 0xbfb8aa3b, v14
	v_mul_f32_e32 v19, 0xbfb8aa3b, v15
	v_exp_f32_e32 v18, v18
	v_exp_f32_e32 v19, v19
	v_mov_b32_dpp v74, v74 row_ror:1 row_mask:0xf bank_mask:0xf
	v_mov_b32_dpp v73, v73 row_ror:15 row_mask:0xf bank_mask:0xf
	v_mov_b32_dpp v75, v75 row_ror:15 row_mask:0xf bank_mask:0xf
	v_pk_add_f32 v[18:19], v[18:19], 1.0 op_sel_hi:[1,0]
	v_cndmask_b32_e64 v80, v38, v42, s[42:43]
	v_rcp_f32_e32 v18, v18
	v_rcp_f32_e32 v19, v19
	v_cndmask_b32_e64 v82, v39, v43, s[42:43]
	v_pk_mul_f32 v[42:43], v[42:43], v[22:23]
	s_waitcnt lgkmcnt(0)
	v_cndmask_b32_e64 v59, 0, v75, s[50:51]
	v_pk_mul_f32 v[14:15], v[14:15], v[18:19]
	v_cndmask_b32_e64 v19, 0, v74, s[48:49]
	v_cndmask_b32_e64 v18, 0, v72, s[48:49]
	v_cndmask_b32_e64 v58, 0, v73, s[50:51]
	v_pk_fma_f32 v[18:19], v[2:3], v[18:19], v[42:43]
	v_cndmask_b32_e64 v81, v38, v48, s[40:41]
	v_pk_fma_f32 v[18:19], v[6:7], v[58:59], v[18:19]
	v_mov_b32_dpp v80, v80 row_ror:1 row_mask:0xf bank_mask:0xf
	v_pk_add_f32 v[18:19], v[10:11], v[18:19]
	v_cndmask_b32_e64 v83, v39, v49, s[40:41]
	v_mul_f32_e32 v42, 0xbfb8aa3b, v18
	v_mul_f32_e32 v43, 0xbfb8aa3b, v19
	v_exp_f32_e32 v42, v42
	v_exp_f32_e32 v43, v43
	v_mov_b32_dpp v82, v82 row_ror:1 row_mask:0xf bank_mask:0xf
	v_mov_b32_dpp v81, v81 row_ror:15 row_mask:0xf bank_mask:0xf
	v_mov_b32_dpp v83, v83 row_ror:15 row_mask:0xf bank_mask:0xf
	v_pk_add_f32 v[42:43], v[42:43], 1.0 op_sel_hi:[1,0]
	v_cndmask_b32_e64 v84, v48, v38, s[42:43]
	v_rcp_f32_e32 v42, v42
	v_rcp_f32_e32 v43, v43
	v_pk_mul_f32 v[38:39], v[38:39], v[22:23]
	v_mov_b32_dpp v84, v84 row_ror:1 row_mask:0xf bank_mask:0xf
	v_pk_mul_f32 v[22:23], v[48:49], v[22:23]
	v_pk_mul_f32 v[18:19], v[18:19], v[42:43]
	s_waitcnt lgkmcnt(0)
	v_cndmask_b32_e64 v43, 0, v83, s[54:55]
	v_pk_mul_f32 v[18:19], v[34:35], v[18:19]
	v_cndmask_b32_e64 v35, 0, v82, s[52:53]
	v_cndmask_b32_e64 v34, 0, v80, s[52:53]
	v_cndmask_b32_e64 v42, 0, v81, s[54:55]
	v_pk_fma_f32 v[34:35], v[2:3], v[34:35], v[38:39]
	v_pk_mul_f32 v[68:69], v[60:61], v[24:25]
	v_pk_fma_f32 v[34:35], v[6:7], v[42:43], v[34:35]
	v_cndmask_b32_e64 v16, v40, v16, s[40:41]
	v_pk_add_f32 v[34:35], v[10:11], v[34:35]
	v_pk_mul_f32 v[14:15], v[50:51], v[14:15]
	v_mul_f32_e32 v38, 0xbfb8aa3b, v34
	v_mul_f32_e32 v39, 0xbfb8aa3b, v35
	v_exp_f32_e32 v38, v38
	v_exp_f32_e32 v39, v39
	v_pk_mul_f32 v[50:51], v[44:45], v[24:25]
	v_pk_mul_f32 v[58:59], v[28:29], v[24:25]
	v_pk_mul_f32 v[24:25], v[40:41], v[24:25]
	v_pk_add_f32 v[38:39], v[38:39], 1.0 op_sel_hi:[1,0]
	v_cndmask_b32_e64 v17, v41, v17, s[40:41]
	v_rcp_f32_e32 v38, v38
	v_rcp_f32_e32 v39, v39
	s_movk_i32 s0, 0xfe
	v_pk_mul_f32 v[34:35], v[34:35], v[38:39]
	s_nop 0
	v_pk_mul_f32 v[32:33], v[32:33], v[34:35]
	v_cndmask_b32_e64 v35, 0, v86, s[56:57]
	v_cndmask_b32_e64 v34, 0, v84, s[56:57]
	v_cndmask_b32_e64 v39, 0, v87, s[58:59]
	v_cndmask_b32_e64 v38, 0, v85, s[58:59]
	v_pk_fma_f32 v[2:3], v[2:3], v[34:35], v[22:23]
	v_cndmask_b32_e64 v22, v45, v61, s[42:43]
	v_pk_fma_f32 v[2:3], v[6:7], v[38:39], v[2:3]
	v_cndmask_b32_e64 v23, v45, v29, s[40:41]
	v_pk_add_f32 v[2:3], v[10:11], v[2:3]
	v_cndmask_b32_e64 v11, v61, v45, s[40:41]
	v_mul_f32_e32 v6, 0xbfb8aa3b, v2
	v_mul_f32_e32 v7, 0xbfb8aa3b, v3
	v_exp_f32_e32 v6, v6
	v_exp_f32_e32 v7, v7
	v_mov_b32_dpp v11, v11 row_ror:15 row_mask:0xf bank_mask:0xf
	v_mov_b32_dpp v22, v22 row_ror:1 row_mask:0xf bank_mask:0xf
	v_mov_b32_dpp v23, v23 row_ror:15 row_mask:0xf bank_mask:0xf
	v_pk_add_f32 v[6:7], v[6:7], 1.0 op_sel_hi:[1,0]
	v_cndmask_b32_e64 v34, v28, v44, s[42:43]
	v_rcp_f32_e32 v6, v6
	v_rcp_f32_e32 v7, v7
	s_waitcnt lgkmcnt(0)
	v_cndmask_b32_e64 v11, v11, 0, s[44:45]
	v_cndmask_b32_e64 v35, v28, v40, s[40:41]
	v_cndmask_b32_e64 v38, v29, v45, s[42:43]
	v_pk_mul_f32 v[2:3], v[2:3], v[6:7]
	v_cndmask_b32_e64 v7, v60, v44, s[40:41]
	v_cndmask_b32_e64 v6, v60, v20, s[42:43]
	s_nop 0
	v_mov_b32_dpp v10, v7 row_ror:15 row_mask:0xf bank_mask:0xf
	v_cndmask_b32_e64 v7, v61, v21, s[42:43]
	v_mov_b32_dpp v6, v6 row_ror:1 row_mask:0xf bank_mask:0xf
	s_nop 0
	v_mov_b32_dpp v7, v7 row_ror:1 row_mask:0xf bank_mask:0xf
	v_cndmask_b32_e64 v20, v44, v60, s[42:43]
	s_waitcnt lgkmcnt(0)
	v_cndmask_b32_e64 v10, v10, 0, s[44:45]
	v_cndmask_b32_e64 v21, v44, v28, s[40:41]
	v_cndmask_b32_e64 v6, 0, v6, s[46:47]
	v_cndmask_b32_e64 v7, 0, v7, s[46:47]
	v_pk_fma_f32 v[6:7], v[4:5], v[6:7], v[68:69]
	v_mov_b32_dpp v20, v20 row_ror:1 row_mask:0xf bank_mask:0xf
	v_pk_fma_f32 v[6:7], v[8:9], v[10:11], v[6:7]
	v_mov_b32_dpp v21, v21 row_ror:15 row_mask:0xf bank_mask:0xf
	v_pk_add_f32 v[6:7], v[12:13], v[6:7]
	v_cndmask_b32_e64 v28, v40, v28, s[42:43]
	v_mul_f32_e32 v10, 0xbfb8aa3b, v6
	v_mul_f32_e32 v11, 0xbfb8aa3b, v7
	v_exp_f32_e32 v10, v10
	v_exp_f32_e32 v11, v11
	v_mov_b32_dpp v40, v16 row_ror:15 row_mask:0xf bank_mask:0xf
	v_cndmask_b32_e64 v16, v41, v29, s[42:43]
	v_cndmask_b32_e64 v39, v29, v41, s[40:41]
	v_pk_add_f32 v[10:11], v[10:11], 1.0 op_sel_hi:[1,0]
	v_mov_b32_dpp v29, v16 row_ror:1 row_mask:0xf bank_mask:0xf
	v_rcp_f32_e32 v10, v10
	v_rcp_f32_e32 v11, v11
	v_mov_b32_dpp v41, v17 row_ror:15 row_mask:0xf bank_mask:0xf
	v_cndmask_b32_e64 v17, 0, v23, s[50:51]
	s_waitcnt lgkmcnt(0)
	v_cndmask_b32_e64 v16, 0, v21, s[50:51]
	v_pk_mul_f32 v[6:7], v[6:7], v[10:11]
	v_cndmask_b32_e64 v11, 0, v22, s[48:49]
	v_cndmask_b32_e64 v10, 0, v20, s[48:49]
	v_pk_fma_f32 v[10:11], v[4:5], v[10:11], v[50:51]
	v_mov_b32_dpp v34, v34 row_ror:1 row_mask:0xf bank_mask:0xf
	v_pk_fma_f32 v[10:11], v[8:9], v[16:17], v[10:11]
	v_mov_b32_dpp v38, v38 row_ror:1 row_mask:0xf bank_mask:0xf
	v_pk_add_f32 v[10:11], v[12:13], v[10:11]
	v_mov_b32_dpp v35, v35 row_ror:15 row_mask:0xf bank_mask:0xf
	v_mul_f32_e32 v16, 0xbfb8aa3b, v10
	v_mul_f32_e32 v17, 0xbfb8aa3b, v11
	v_exp_f32_e32 v16, v16
	v_exp_f32_e32 v17, v17
	v_mov_b32_dpp v39, v39 row_ror:15 row_mask:0xf bank_mask:0xf
	s_waitcnt lgkmcnt(0)
	v_cndmask_b32_e64 v20, 0, v35, s[54:55]
	v_mov_b32_dpp v28, v28 row_ror:1 row_mask:0xf bank_mask:0xf
	v_pk_add_f32 v[16:17], v[16:17], 1.0 op_sel_hi:[1,0]
	v_cndmask_b32_e64 v23, 0, v41, s[58:59]
	v_rcp_f32_e32 v16, v16
	v_rcp_f32_e32 v17, v17
	v_cndmask_b32_e64 v21, 0, v39, s[54:55]
	v_cndmask_b32_e64 v22, 0, v40, s[58:59]
	v_pk_mul_f32 v[2:3], v[46:47], v[2:3]
	v_pk_mul_f32 v[10:11], v[10:11], v[16:17]
	v_cndmask_b32_e64 v17, 0, v38, s[52:53]
	v_cndmask_b32_e64 v16, 0, v34, s[52:53]
	v_pk_fma_f32 v[16:17], v[4:5], v[16:17], v[58:59]
	v_pk_mul_f32 v[6:7], v[52:53], v[6:7]
	v_pk_fma_f32 v[16:17], v[8:9], v[20:21], v[16:17]
	v_pk_mul_f32 v[10:11], v[36:37], v[10:11]
	v_pk_add_f32 v[16:17], v[12:13], v[16:17]
	s_nop 0
	v_mul_f32_e32 v20, 0xbfb8aa3b, v16
	v_mul_f32_e32 v21, 0xbfb8aa3b, v17
	v_exp_f32_e32 v20, v20
	v_exp_f32_e32 v21, v21
	s_nop 0
	v_pk_add_f32 v[20:21], v[20:21], 1.0 op_sel_hi:[1,0]
	s_nop 0
	v_rcp_f32_e32 v20, v20
	v_rcp_f32_e32 v21, v21
	s_nop 0
	v_pk_mul_f32 v[16:17], v[16:17], v[20:21]
	v_cndmask_b32_e64 v21, 0, v29, s[56:57]
	s_waitcnt lgkmcnt(0)
	v_cndmask_b32_e64 v20, 0, v28, s[56:57]
	v_pk_fma_f32 v[4:5], v[4:5], v[20:21], v[24:25]
	v_pk_mul_f32 v[16:17], v[26:27], v[16:17]
	v_pk_fma_f32 v[4:5], v[8:9], v[22:23], v[4:5]
	s_nop 0
	v_pk_add_f32 v[4:5], v[12:13], v[4:5]
	s_nop 0
	v_mul_f32_e32 v8, 0xbfb8aa3b, v4
	v_mul_f32_e32 v9, 0xbfb8aa3b, v5
	v_exp_f32_e32 v8, v8
	v_exp_f32_e32 v9, v9
	s_nop 0
	v_pk_add_f32 v[8:9], v[8:9], 1.0 op_sel_hi:[1,0]
	s_nop 0
	v_rcp_f32_e32 v8, v8
	v_rcp_f32_e32 v9, v9
	s_nop 0
	v_pk_mul_f32 v[4:5], v[4:5], v[8:9]
	v_add_u32_e32 v8, 0x7f, v189
	v_cmp_gt_u32_e32 vcc, s0, v8
	v_cmp_gt_i32_e64 s[0:1], s10, v190
	v_pk_mul_f32 v[4:5], v[30:31], v[4:5]
	s_and_b64 s[40:41], vcc, s[0:1]
	s_and_saveexec_b64 s[0:1], s[40:41]
	s_cbranch_execz .LBB0_1366
	s_movk_i32 s40, 0xb00
	v_cvt_pk_bf16_f32 v14, v14, v15
	v_cvt_pk_bf16_f32 v15, v6, v7
	v_mul_lo_u32 v6, v190, s40
	v_cvt_pk_bf16_f32 v12, v66, v67
	v_cvt_pk_bf16_f32 v13, v56, v57
	v_add_lshl_u32 v6, v138, v6, 1
	global_store_dwordx4 v6, v[12:15], s[92:93] sc1
.LBB0_1366:
	s_or_b64 exec, exec, s[0:1]
	s_movk_i32 s42, 0xff
	v_cmp_gt_u32_e32 vcc, s42, v192
	v_cmp_gt_i32_e64 s[0:1], s10, v191
	s_and_b64 s[40:41], vcc, s[0:1]
	s_and_saveexec_b64 s[0:1], s[40:41]
	s_cbranch_execz .LBB0_1368
	s_movk_i32 s40, 0xb00
	v_cvt_pk_bf16_f32 v9, v10, v11
	v_mul_lo_u32 v10, v191, s40
	v_cvt_pk_bf16_f32 v6, v70, v71
	v_cvt_pk_bf16_f32 v7, v54, v55
	v_cvt_pk_bf16_f32 v8, v18, v19
	v_add_lshl_u32 v10, v138, v10, 1
	global_store_dwordx4 v10, v[6:9], s[92:93] sc1
.LBB0_1368:
	s_or_b64 exec, exec, s[0:1]
	v_cmp_gt_u32_e32 vcc, s42, v194
	v_cmp_gt_i32_e64 s[0:1], s10, v193
	s_and_b64 s[40:41], vcc, s[0:1]
	s_and_saveexec_b64 s[0:1], s[40:41]
	s_cbranch_execz .LBB0_1370
	s_movk_i32 s40, 0xb00
	v_mul_lo_u32 v10, v193, s40
	v_cvt_pk_bf16_f32 v6, v76, v77
	v_cvt_pk_bf16_f32 v7, v62, v63
	v_cvt_pk_bf16_f32 v8, v32, v33
	v_cvt_pk_bf16_f32 v9, v16, v17
	v_add_lshl_u32 v10, v138, v10, 1
	global_store_dwordx4 v10, v[6:9], s[92:93] sc1
.LBB0_1370:
	s_or_b64 exec, exec, s[0:1]
	v_cmp_gt_u32_e32 vcc, s42, v196
	v_cmp_gt_i32_e64 s[0:1], s10, v195
	s_and_b64 s[40:41], vcc, s[0:1]
	s_and_saveexec_b64 s[0:1], s[40:41]
	s_cbranch_execz .LBB0_1372
	s_movk_i32 s40, 0xb00
	v_cvt_pk_bf16_f32 v8, v2, v3
	v_mul_lo_u32 v2, v195, s40
	v_cvt_pk_bf16_f32 v6, v78, v79
	v_cvt_pk_bf16_f32 v7, v64, v65
	v_cvt_pk_bf16_f32 v9, v4, v5
	v_add_lshl_u32 v2, v138, v2, 1
	global_store_dwordx4 v2, v[6:9], s[92:93] sc1
